# S5 chunk scan: chunk-state LDS reads issued four steps ahead of the running state
# speedup vs baseline: 1.0001x; 1.0001x over previous
.LBB0_443:
	s_mov_b32 s7, 0
	s_mov_b32 s6, 0xfc00000
	v_lshl_add_u64 v[50:51], v[48:49], 0, s[6:7]
	global_load_dwordx4 v[76:79], v[50:51], off
	s_mov_b32 s6, 0xfc02000
	v_lshl_add_u64 v[50:51], v[48:49], 0, s[6:7]
	global_load_dwordx4 v[80:83], v[50:51], off
	s_mov_b32 s6, 0xfc04000
	v_lshl_add_u64 v[50:51], v[48:49], 0, s[6:7]
	global_load_dwordx4 v[84:87], v[50:51], off
	s_mov_b32 s6, 0xfc06000
	v_lshl_add_u64 v[50:51], v[48:49], 0, s[6:7]
	global_load_dwordx4 v[88:91], v[50:51], off
	s_mov_b32 s6, 0xfc08000
	v_lshl_add_u64 v[50:51], v[48:49], 0, s[6:7]
	global_load_dwordx4 v[92:95], v[50:51], off
	s_mov_b32 s6, 0xfc0a000
	v_lshl_add_u64 v[50:51], v[48:49], 0, s[6:7]
	global_load_dwordx4 v[96:99], v[50:51], off
	s_mov_b32 s6, 0xfc0c000
	v_lshl_add_u64 v[50:51], v[48:49], 0, s[6:7]
	global_load_dwordx4 v[100:103], v[50:51], off
	s_mov_b32 s6, 0xfc0e000
	v_lshl_add_u64 v[50:51], v[48:49], 0, s[6:7]
	global_load_dwordx4 v[104:107], v[50:51], off
	s_mov_b32 s6, 0xfc10000
	v_lshl_add_u64 v[50:51], v[48:49], 0, s[6:7]
	global_load_dwordx4 v[108:111], v[50:51], off
	s_mov_b32 s6, 0xfc12000
	v_lshl_add_u64 v[50:51], v[48:49], 0, s[6:7]
	global_load_dwordx4 v[112:115], v[50:51], off
	s_mov_b32 s6, 0xfc14000
	v_lshl_add_u64 v[50:51], v[48:49], 0, s[6:7]
	global_load_dwordx4 v[116:119], v[50:51], off
	s_mov_b32 s6, 0xfc16000
	v_lshl_add_u64 v[50:51], v[48:49], 0, s[6:7]
	global_load_dwordx4 v[120:123], v[50:51], off
	s_mov_b32 s6, 0xfc18000
	v_lshl_add_u64 v[50:51], v[48:49], 0, s[6:7]
	global_load_dwordx4 v[124:127], v[50:51], off
	s_mov_b32 s6, 0xfc1a000
	v_lshl_add_u64 v[50:51], v[48:49], 0, s[6:7]
	global_load_dwordx4 v[128:131], v[50:51], off
	s_mov_b32 s6, 0xfc1c000
	v_lshl_add_u64 v[50:51], v[48:49], 0, s[6:7]
	global_load_dwordx4 v[132:135], v[50:51], off
	s_mov_b32 s6, 0xfc1e000
	v_lshl_add_u64 v[50:51], v[48:49], 0, s[6:7]
	global_load_dwordx4 v[136:139], v[50:51], off
	s_mov_b32 s6, 0xfc20000
	v_lshl_add_u64 v[50:51], v[48:49], 0, s[6:7]
	global_load_dwordx4 v[140:143], v[50:51], off
	s_mov_b32 s6, 0xfc22000
	v_lshl_add_u64 v[50:51], v[48:49], 0, s[6:7]
	global_load_dwordx4 v[144:147], v[50:51], off
	s_mov_b32 s6, 0xfc24000
	v_lshl_add_u64 v[50:51], v[48:49], 0, s[6:7]
	global_load_dwordx4 v[148:151], v[50:51], off
	s_mov_b32 s6, 0xfc26000
	v_lshl_add_u64 v[50:51], v[48:49], 0, s[6:7]
	global_load_dwordx4 v[152:155], v[50:51], off
	s_mov_b32 s6, 0xfc28000
	v_lshl_add_u64 v[50:51], v[48:49], 0, s[6:7]
	global_load_dwordx4 v[156:159], v[50:51], off
	s_mov_b32 s6, 0xfc2a000
	v_lshl_add_u64 v[50:51], v[48:49], 0, s[6:7]
	global_load_dwordx4 v[160:163], v[50:51], off
	s_mov_b32 s6, 0xfc2c000
	v_lshl_add_u64 v[50:51], v[48:49], 0, s[6:7]
	global_load_dwordx4 v[164:167], v[50:51], off
	s_mov_b32 s6, 0xfc2e000
	v_lshl_add_u64 v[50:51], v[48:49], 0, s[6:7]
	global_load_dwordx4 v[168:171], v[50:51], off
	s_mov_b32 s6, 0xfc30000
	v_lshl_add_u64 v[50:51], v[48:49], 0, s[6:7]
	global_load_dwordx4 v[172:175], v[50:51], off
	s_mov_b32 s6, 0xfc32000
	v_lshl_add_u64 v[50:51], v[48:49], 0, s[6:7]
	global_load_dwordx4 v[176:179], v[50:51], off
	s_mov_b32 s6, 0xfc34000
	v_lshl_add_u64 v[50:51], v[48:49], 0, s[6:7]
	global_load_dwordx4 v[180:183], v[50:51], off
	s_mov_b32 s6, 0xfc36000
	v_lshl_add_u64 v[50:51], v[48:49], 0, s[6:7]
	global_load_dwordx4 v[184:187], v[50:51], off
	s_mov_b32 s6, 0xfc38000
	v_lshl_add_u64 v[50:51], v[48:49], 0, s[6:7]
	global_load_dwordx4 v[188:191], v[50:51], off
	s_mov_b32 s6, 0xfc3a000
	v_lshl_add_u64 v[50:51], v[48:49], 0, s[6:7]
	global_load_dwordx4 v[192:195], v[50:51], off
	s_mov_b32 s6, 0xfc3c000
	v_lshl_add_u64 v[50:51], v[48:49], 0, s[6:7]
	global_load_dwordx4 v[196:199], v[50:51], off
	s_mov_b32 s6, 0xfc3e000
	v_lshl_add_u64 v[50:51], v[48:49], 0, s[6:7]
	global_load_dwordx4 v[200:203], v[50:51], off
	ds_read_b128 v[204:207], v54 offset:0
	ds_read_b128 v[208:211], v54 offset:33280
	ds_read_b128 v[212:215], v55 offset:0
	ds_read_b128 v[216:219], v54 offset:32
	ds_read_b128 v[220:223], v54 offset:33312
	ds_read_b128 v[224:227], v55 offset:32
	s_waitcnt vmcnt(31) lgkmcnt(3)
	v_mfma_f32_32x32x16_bf16 v[0:15], v[76:79], v[204:207], v[0:15]
	v_mfma_f32_32x32x16_bf16 v[16:31], v[76:79], v[208:211], v[16:31]
	v_mfma_f32_32x32x16_bf16 v[32:47], v[76:79], v[212:215], v[32:47]
	ds_read_b128 v[204:207], v54 offset:64
	ds_read_b128 v[208:211], v54 offset:33344
	ds_read_b128 v[212:215], v55 offset:64
	s_waitcnt vmcnt(30) lgkmcnt(3)
	v_mfma_f32_32x32x16_bf16 v[0:15], v[80:83], v[216:219], v[0:15]
	v_mfma_f32_32x32x16_bf16 v[16:31], v[80:83], v[220:223], v[16:31]
	v_mfma_f32_32x32x16_bf16 v[32:47], v[80:83], v[224:227], v[32:47]
	ds_read_b128 v[216:219], v54 offset:96
	ds_read_b128 v[220:223], v54 offset:33376
	ds_read_b128 v[224:227], v55 offset:96
	s_waitcnt vmcnt(29) lgkmcnt(3)
	v_mfma_f32_32x32x16_bf16 v[0:15], v[84:87], v[204:207], v[0:15]
	v_mfma_f32_32x32x16_bf16 v[16:31], v[84:87], v[208:211], v[16:31]
	v_mfma_f32_32x32x16_bf16 v[32:47], v[84:87], v[212:215], v[32:47]
	ds_read_b128 v[204:207], v54 offset:128
	ds_read_b128 v[208:211], v54 offset:33408
	ds_read_b128 v[212:215], v55 offset:128
	s_waitcnt vmcnt(28) lgkmcnt(3)
	v_mfma_f32_32x32x16_bf16 v[0:15], v[88:91], v[216:219], v[0:15]
	v_mfma_f32_32x32x16_bf16 v[16:31], v[88:91], v[220:223], v[16:31]
	v_mfma_f32_32x32x16_bf16 v[32:47], v[88:91], v[224:227], v[32:47]
	ds_read_b128 v[216:219], v54 offset:160
	ds_read_b128 v[220:223], v54 offset:33440
	ds_read_b128 v[224:227], v55 offset:160
	s_waitcnt vmcnt(27) lgkmcnt(3)
	v_mfma_f32_32x32x16_bf16 v[0:15], v[92:95], v[204:207], v[0:15]
	v_mfma_f32_32x32x16_bf16 v[16:31], v[92:95], v[208:211], v[16:31]
	v_mfma_f32_32x32x16_bf16 v[32:47], v[92:95], v[212:215], v[32:47]
	ds_read_b128 v[204:207], v54 offset:192
	ds_read_b128 v[208:211], v54 offset:33472
	ds_read_b128 v[212:215], v55 offset:192
	s_waitcnt vmcnt(26) lgkmcnt(3)
	v_mfma_f32_32x32x16_bf16 v[0:15], v[96:99], v[216:219], v[0:15]
	v_mfma_f32_32x32x16_bf16 v[16:31], v[96:99], v[220:223], v[16:31]
	v_mfma_f32_32x32x16_bf16 v[32:47], v[96:99], v[224:227], v[32:47]
	ds_read_b128 v[216:219], v54 offset:224
	ds_read_b128 v[220:223], v54 offset:33504
	ds_read_b128 v[224:227], v55 offset:224
	s_waitcnt vmcnt(25) lgkmcnt(3)
	v_mfma_f32_32x32x16_bf16 v[0:15], v[100:103], v[204:207], v[0:15]
	v_mfma_f32_32x32x16_bf16 v[16:31], v[100:103], v[208:211], v[16:31]
	v_mfma_f32_32x32x16_bf16 v[32:47], v[100:103], v[212:215], v[32:47]
	ds_read_b128 v[204:207], v54 offset:256
	ds_read_b128 v[208:211], v54 offset:33536
	ds_read_b128 v[212:215], v55 offset:256
	s_waitcnt vmcnt(24) lgkmcnt(3)
	v_mfma_f32_32x32x16_bf16 v[0:15], v[104:107], v[216:219], v[0:15]
	v_mfma_f32_32x32x16_bf16 v[16:31], v[104:107], v[220:223], v[16:31]
	v_mfma_f32_32x32x16_bf16 v[32:47], v[104:107], v[224:227], v[32:47]
	ds_read_b128 v[216:219], v54 offset:288
	ds_read_b128 v[220:223], v54 offset:33568
	ds_read_b128 v[224:227], v55 offset:288
	s_waitcnt vmcnt(23) lgkmcnt(3)
	v_mfma_f32_32x32x16_bf16 v[0:15], v[108:111], v[204:207], v[0:15]
	v_mfma_f32_32x32x16_bf16 v[16:31], v[108:111], v[208:211], v[16:31]
	v_mfma_f32_32x32x16_bf16 v[32:47], v[108:111], v[212:215], v[32:47]
	ds_read_b128 v[204:207], v54 offset:320
	ds_read_b128 v[208:211], v54 offset:33600
	ds_read_b128 v[212:215], v55 offset:320
	s_waitcnt vmcnt(22) lgkmcnt(3)
	v_mfma_f32_32x32x16_bf16 v[0:15], v[112:115], v[216:219], v[0:15]
	v_mfma_f32_32x32x16_bf16 v[16:31], v[112:115], v[220:223], v[16:31]
	v_mfma_f32_32x32x16_bf16 v[32:47], v[112:115], v[224:227], v[32:47]
	ds_read_b128 v[216:219], v54 offset:352
	ds_read_b128 v[220:223], v54 offset:33632
	ds_read_b128 v[224:227], v55 offset:352
	s_waitcnt vmcnt(21) lgkmcnt(3)
	v_mfma_f32_32x32x16_bf16 v[0:15], v[116:119], v[204:207], v[0:15]
	v_mfma_f32_32x32x16_bf16 v[16:31], v[116:119], v[208:211], v[16:31]
	v_mfma_f32_32x32x16_bf16 v[32:47], v[116:119], v[212:215], v[32:47]
	ds_read_b128 v[204:207], v54 offset:384
	ds_read_b128 v[208:211], v54 offset:33664
	ds_read_b128 v[212:215], v55 offset:384
	s_waitcnt vmcnt(20) lgkmcnt(3)
	v_mfma_f32_32x32x16_bf16 v[0:15], v[120:123], v[216:219], v[0:15]
	v_mfma_f32_32x32x16_bf16 v[16:31], v[120:123], v[220:223], v[16:31]
	v_mfma_f32_32x32x16_bf16 v[32:47], v[120:123], v[224:227], v[32:47]
	ds_read_b128 v[216:219], v54 offset:416
	ds_read_b128 v[220:223], v54 offset:33696
	ds_read_b128 v[224:227], v55 offset:416
	s_waitcnt vmcnt(19) lgkmcnt(3)
	v_mfma_f32_32x32x16_bf16 v[0:15], v[124:127], v[204:207], v[0:15]
	v_mfma_f32_32x32x16_bf16 v[16:31], v[124:127], v[208:211], v[16:31]
	v_mfma_f32_32x32x16_bf16 v[32:47], v[124:127], v[212:215], v[32:47]
	ds_read_b128 v[204:207], v54 offset:448
	ds_read_b128 v[208:211], v54 offset:33728
	ds_read_b128 v[212:215], v55 offset:448
	s_waitcnt vmcnt(18) lgkmcnt(3)
	v_mfma_f32_32x32x16_bf16 v[0:15], v[128:131], v[216:219], v[0:15]
	v_mfma_f32_32x32x16_bf16 v[16:31], v[128:131], v[220:223], v[16:31]
	v_mfma_f32_32x32x16_bf16 v[32:47], v[128:131], v[224:227], v[32:47]
	ds_read_b128 v[216:219], v54 offset:480
	ds_read_b128 v[220:223], v54 offset:33760
	ds_read_b128 v[224:227], v55 offset:480
	s_waitcnt vmcnt(17) lgkmcnt(3)
	v_mfma_f32_32x32x16_bf16 v[0:15], v[132:135], v[204:207], v[0:15]
	v_mfma_f32_32x32x16_bf16 v[16:31], v[132:135], v[208:211], v[16:31]
	v_mfma_f32_32x32x16_bf16 v[32:47], v[132:135], v[212:215], v[32:47]
	ds_read_b128 v[204:207], v54 offset:512
	ds_read_b128 v[208:211], v54 offset:33792
	ds_read_b128 v[212:215], v55 offset:512
	s_waitcnt vmcnt(16) lgkmcnt(3)
	v_mfma_f32_32x32x16_bf16 v[0:15], v[136:139], v[216:219], v[0:15]
	v_mfma_f32_32x32x16_bf16 v[16:31], v[136:139], v[220:223], v[16:31]
	v_mfma_f32_32x32x16_bf16 v[32:47], v[136:139], v[224:227], v[32:47]
	ds_read_b128 v[216:219], v54 offset:544
	ds_read_b128 v[220:223], v54 offset:33824
	ds_read_b128 v[224:227], v55 offset:544
	s_waitcnt vmcnt(15) lgkmcnt(3)
	v_mfma_f32_32x32x16_bf16 v[0:15], v[140:143], v[204:207], v[0:15]
	v_mfma_f32_32x32x16_bf16 v[16:31], v[140:143], v[208:211], v[16:31]
	v_mfma_f32_32x32x16_bf16 v[32:47], v[140:143], v[212:215], v[32:47]
	ds_read_b128 v[204:207], v54 offset:576
	ds_read_b128 v[208:211], v54 offset:33856
	ds_read_b128 v[212:215], v55 offset:576
	s_waitcnt vmcnt(14) lgkmcnt(3)
	v_mfma_f32_32x32x16_bf16 v[0:15], v[144:147], v[216:219], v[0:15]
	v_mfma_f32_32x32x16_bf16 v[16:31], v[144:147], v[220:223], v[16:31]
	v_mfma_f32_32x32x16_bf16 v[32:47], v[144:147], v[224:227], v[32:47]
	ds_read_b128 v[216:219], v54 offset:608
	ds_read_b128 v[220:223], v54 offset:33888
	ds_read_b128 v[224:227], v55 offset:608
	s_waitcnt vmcnt(13) lgkmcnt(3)
	v_mfma_f32_32x32x16_bf16 v[0:15], v[148:151], v[204:207], v[0:15]
	v_mfma_f32_32x32x16_bf16 v[16:31], v[148:151], v[208:211], v[16:31]
	v_mfma_f32_32x32x16_bf16 v[32:47], v[148:151], v[212:215], v[32:47]
	ds_read_b128 v[204:207], v54 offset:640
	ds_read_b128 v[208:211], v54 offset:33920
	ds_read_b128 v[212:215], v55 offset:640
	s_waitcnt vmcnt(12) lgkmcnt(3)
	v_mfma_f32_32x32x16_bf16 v[0:15], v[152:155], v[216:219], v[0:15]
	v_mfma_f32_32x32x16_bf16 v[16:31], v[152:155], v[220:223], v[16:31]
	v_mfma_f32_32x32x16_bf16 v[32:47], v[152:155], v[224:227], v[32:47]
	ds_read_b128 v[216:219], v54 offset:672
	ds_read_b128 v[220:223], v54 offset:33952
	ds_read_b128 v[224:227], v55 offset:672
	s_waitcnt vmcnt(11) lgkmcnt(3)
	v_mfma_f32_32x32x16_bf16 v[0:15], v[156:159], v[204:207], v[0:15]
	v_mfma_f32_32x32x16_bf16 v[16:31], v[156:159], v[208:211], v[16:31]
	v_mfma_f32_32x32x16_bf16 v[32:47], v[156:159], v[212:215], v[32:47]
	ds_read_b128 v[204:207], v54 offset:704
	ds_read_b128 v[208:211], v54 offset:33984
	ds_read_b128 v[212:215], v55 offset:704
	s_waitcnt vmcnt(10) lgkmcnt(3)
	v_mfma_f32_32x32x16_bf16 v[0:15], v[160:163], v[216:219], v[0:15]
	v_mfma_f32_32x32x16_bf16 v[16:31], v[160:163], v[220:223], v[16:31]
	v_mfma_f32_32x32x16_bf16 v[32:47], v[160:163], v[224:227], v[32:47]
	ds_read_b128 v[216:219], v54 offset:736
	ds_read_b128 v[220:223], v54 offset:34016
	ds_read_b128 v[224:227], v55 offset:736
	s_waitcnt vmcnt(9) lgkmcnt(3)
	v_mfma_f32_32x32x16_bf16 v[0:15], v[164:167], v[204:207], v[0:15]
	v_mfma_f32_32x32x16_bf16 v[16:31], v[164:167], v[208:211], v[16:31]
	v_mfma_f32_32x32x16_bf16 v[32:47], v[164:167], v[212:215], v[32:47]
	ds_read_b128 v[204:207], v54 offset:768
	ds_read_b128 v[208:211], v54 offset:34048
	ds_read_b128 v[212:215], v55 offset:768
	s_waitcnt vmcnt(8) lgkmcnt(3)
	v_mfma_f32_32x32x16_bf16 v[0:15], v[168:171], v[216:219], v[0:15]
	v_mfma_f32_32x32x16_bf16 v[16:31], v[168:171], v[220:223], v[16:31]
	v_mfma_f32_32x32x16_bf16 v[32:47], v[168:171], v[224:227], v[32:47]
	ds_read_b128 v[216:219], v54 offset:800
	ds_read_b128 v[220:223], v54 offset:34080
	ds_read_b128 v[224:227], v55 offset:800
	s_waitcnt vmcnt(7) lgkmcnt(3)
	v_mfma_f32_32x32x16_bf16 v[0:15], v[172:175], v[204:207], v[0:15]
	v_mfma_f32_32x32x16_bf16 v[16:31], v[172:175], v[208:211], v[16:31]
	v_mfma_f32_32x32x16_bf16 v[32:47], v[172:175], v[212:215], v[32:47]
	ds_read_b128 v[204:207], v54 offset:832
	ds_read_b128 v[208:211], v54 offset:34112
	ds_read_b128 v[212:215], v55 offset:832
	s_waitcnt vmcnt(6) lgkmcnt(3)
	v_mfma_f32_32x32x16_bf16 v[0:15], v[176:179], v[216:219], v[0:15]
	v_mfma_f32_32x32x16_bf16 v[16:31], v[176:179], v[220:223], v[16:31]
	v_mfma_f32_32x32x16_bf16 v[32:47], v[176:179], v[224:227], v[32:47]
	ds_read_b128 v[216:219], v54 offset:864
	ds_read_b128 v[220:223], v54 offset:34144
	ds_read_b128 v[224:227], v55 offset:864
	s_waitcnt vmcnt(5) lgkmcnt(3)
	v_mfma_f32_32x32x16_bf16 v[0:15], v[180:183], v[204:207], v[0:15]
	v_mfma_f32_32x32x16_bf16 v[16:31], v[180:183], v[208:211], v[16:31]
	v_mfma_f32_32x32x16_bf16 v[32:47], v[180:183], v[212:215], v[32:47]
	ds_read_b128 v[204:207], v54 offset:896
	ds_read_b128 v[208:211], v54 offset:34176
	ds_read_b128 v[212:215], v55 offset:896
	s_waitcnt vmcnt(4) lgkmcnt(3)
	v_mfma_f32_32x32x16_bf16 v[0:15], v[184:187], v[216:219], v[0:15]
	v_mfma_f32_32x32x16_bf16 v[16:31], v[184:187], v[220:223], v[16:31]
	v_mfma_f32_32x32x16_bf16 v[32:47], v[184:187], v[224:227], v[32:47]
	ds_read_b128 v[216:219], v54 offset:928
	ds_read_b128 v[220:223], v54 offset:34208
	ds_read_b128 v[224:227], v55 offset:928
	s_waitcnt vmcnt(3) lgkmcnt(3)
	v_mfma_f32_32x32x16_bf16 v[0:15], v[188:191], v[204:207], v[0:15]
	v_mfma_f32_32x32x16_bf16 v[16:31], v[188:191], v[208:211], v[16:31]
	v_mfma_f32_32x32x16_bf16 v[32:47], v[188:191], v[212:215], v[32:47]
	ds_read_b128 v[204:207], v54 offset:960
	ds_read_b128 v[208:211], v54 offset:34240
	ds_read_b128 v[212:215], v55 offset:960
	s_waitcnt vmcnt(2) lgkmcnt(3)
	v_mfma_f32_32x32x16_bf16 v[0:15], v[192:195], v[216:219], v[0:15]
	v_mfma_f32_32x32x16_bf16 v[16:31], v[192:195], v[220:223], v[16:31]
	v_mfma_f32_32x32x16_bf16 v[32:47], v[192:195], v[224:227], v[32:47]
	ds_read_b128 v[216:219], v54 offset:992
	ds_read_b128 v[220:223], v54 offset:34272
	ds_read_b128 v[224:227], v55 offset:992
	s_waitcnt vmcnt(1) lgkmcnt(3)
	v_mfma_f32_32x32x16_bf16 v[0:15], v[196:199], v[204:207], v[0:15]
	v_mfma_f32_32x32x16_bf16 v[16:31], v[196:199], v[208:211], v[16:31]
	v_mfma_f32_32x32x16_bf16 v[32:47], v[196:199], v[212:215], v[32:47]
	s_waitcnt vmcnt(0) lgkmcnt(0)
	v_mfma_f32_32x32x16_bf16 v[0:15], v[200:203], v[216:219], v[0:15]
	v_mfma_f32_32x32x16_bf16 v[16:31], v[200:203], v[220:223], v[16:31]
	v_mfma_f32_32x32x16_bf16 v[32:47], v[200:203], v[224:227], v[32:47]
	s_movk_i32 s4, 0x48
	v_cmp_gt_u32_e32 vcc, s4, v239
	v_mov_b32_e32 v48, s20
	s_movk_i32 s4, 0x210
	v_lshlrev_b32_e32 v241, 3, v53
	v_mad_u32_u24 v50, v240, s4, v48
	s_and_b32 s6, s24, 0xffffffc0
	v_add_u32_e32 v51, 0x4200, v50
	v_add_u32_e32 v53, 0x8400, v50
	v_cvt_pk_bf16_f32 v48, v0, v1
	v_or_b32_e32 v0, s6, v241
	v_cvt_pk_bf16_f32 v49, v2, v3
	v_add_u32_e32 v1, v50, v0
	v_cvt_pk_bf16_f32 v16, v16, v17
	v_cvt_pk_bf16_f32 v17, v18, v19
	v_add_u32_e32 v2, v51, v0
	v_add_u32_e32 v0, v53, v0
	ds_write_b64 v1, v[48:49]
	ds_write_b64 v2, v[16:17]
	s_and_saveexec_b64 s[4:5], vcc
	v_cvt_pk_bf16_f32 v16, v32, v33
	v_cvt_pk_bf16_f32 v17, v34, v35
	ds_write_b64 v0, v[16:17]
	s_or_b64 exec, exec, s[4:5]
	v_cvt_pk_bf16_f32 v4, v4, v5
	v_cvt_pk_bf16_f32 v5, v6, v7
	ds_write_b64 v1, v[4:5] offset:16
	v_cvt_pk_bf16_f32 v4, v20, v21
	v_cvt_pk_bf16_f32 v5, v22, v23
	ds_write_b64 v2, v[4:5] offset:16
	s_and_saveexec_b64 s[4:5], vcc
	v_cvt_pk_bf16_f32 v4, v36, v37
	v_cvt_pk_bf16_f32 v5, v38, v39
	ds_write_b64 v0, v[4:5] offset:16
	s_or_b64 exec, exec, s[4:5]
	v_cvt_pk_bf16_f32 v4, v8, v9
	v_cvt_pk_bf16_f32 v5, v10, v11
	ds_write_b64 v1, v[4:5] offset:32
	v_cvt_pk_bf16_f32 v4, v24, v25
	v_cvt_pk_bf16_f32 v5, v26, v27
	ds_write_b64 v2, v[4:5] offset:32
	s_and_saveexec_b64 s[4:5], vcc
	v_cvt_pk_bf16_f32 v4, v40, v41
	v_cvt_pk_bf16_f32 v5, v42, v43
	ds_write_b64 v0, v[4:5] offset:32
	s_or_b64 exec, exec, s[4:5]
	v_cvt_pk_bf16_f32 v4, v12, v13
	v_cvt_pk_bf16_f32 v5, v14, v15
	ds_write_b64 v1, v[4:5] offset:48
	v_cvt_pk_bf16_f32 v4, v28, v29
	v_cvt_pk_bf16_f32 v5, v30, v31
	ds_write_b64 v2, v[4:5] offset:48
	s_and_saveexec_b64 s[4:5], vcc
	v_cvt_pk_bf16_f32 v2, v44, v45
	v_cvt_pk_bf16_f32 v3, v46, v47
	ds_write_b64 v0, v[2:3] offset:48
	s_or_b64 exec, exec, s[4:5]
	s_cmp_gt_i32 s1, 1
	s_waitcnt lgkmcnt(0)
	s_barrier
	s_cbranch_scc1 .LBB0_456
	s_or_b32 s4, s6, s23
	v_lshl_or_b32 v0, s4, 6, v235
	v_readlane_b32 s68, v253, 4
	s_ashr_i32 s5, s4, 31
	v_ashrrev_i32_e32 v1, 31, v0
	v_readlane_b32 s74, v253, 10
	s_lshl_b64 s[4:5], s[4:5], 2
	v_lshlrev_b64 v[0:1], 2, v[0:1]
	v_readlane_b32 s70, v253, 6
	v_readlane_b32 s71, v253, 7
	v_readlane_b32 s72, v253, 8
	v_readlane_b32 s73, v253, 9
	v_readlane_b32 s75, v253, 11
	s_add_u32 s4, s74, s4
	v_lshl_add_u64 v[2:3], s[70:71], 0, v[0:1]
	v_lshl_add_u64 v[0:1], s[72:73], 0, v[0:1]
	s_addc_u32 s5, s75, s5
	global_load_dword v1, v[0:1], off
	v_mov_b32_e32 v4, 0
	global_load_dword v0, v233, s[4:5]
	s_mov_b32 s4, 0x42000000
	global_load_dword v2, v[2:3], off
	s_mov_b32 s6, 0
	s_mov_b32 s7, -3
	v_mov_b32_e32 v5, v4
	v_readlane_b32 s69, v253, 5
	v_readlane_b32 s76, v253, 12
	v_readlane_b32 s77, v253, 13
	v_readlane_b32 s78, v253, 14
	v_readlane_b32 s79, v253, 15
	v_readlane_b32 s80, v253, 16
	v_readlane_b32 s81, v253, 17
	v_readlane_b32 s82, v253, 18
	v_readlane_b32 s83, v253, 19
	s_waitcnt vmcnt(1)
	v_mul_f32_e32 v0, 0x3fb8aa3b, v0
	v_exp_f32_e32 v3, v0
	s_waitcnt vmcnt(0)
	v_mul_f32_e32 v0, 0x42000000, v2
	v_mul_f32_e32 v1, v1, v3
	v_mul_f32_e32 v1, 0.15915494, v1
	v_mul_f32_e32 v2, 0x42000000, v1
	v_mul_f32_e32 v0, v0, v3
	v_floor_f32_e32 v2, v2
	v_mul_f32_e32 v0, 0x3fb8aa3b, v0
	v_fma_f32 v1, v1, s4, -v2
	v_exp_f32_e32 v0, v0
	v_cos_f32_e32 v2, v1
	v_sin_f32_e32 v3, v1
	s_lshl_b32 s4, s1, 8
	s_add_i32 s4, s4, 0
	s_add_i32 s4, s4, 0x12800
	v_pk_mul_f32 v[0:1], v[0:1], v[2:3] op_sel_hi:[0,1]
	s_cmp_lt_u32 s24, 64
	v_lshl_add_u32 v6, v235, 1, s4
	s_cselect_b64 s[4:5], -1, 0
	v_pk_mov_b32 v[2:3], v[0:1], v[0:1] op_sel:[1,0]
	s_and_b64 s[14:15], s[4:5], exec
	s_movk_i32 s12, 0x210
	s_mov_b32 s18, 0xfffffdf0
	s_cselect_b32 s12, s12, s18
	s_mov_b32 s13, 0x9480
	s_cselect_b32 s13, 0, s13
	s_movk_i32 s18, 0xe70
	s_cselect_b32 s18, 0, s18
	v_add_u32_e32 v7, s18, v6
	v_mov_b32_e32 v10, v7
	ds_read_u16 v245, v10 offset:128
	ds_read_u16 v244, v10
	v_add_u32_e32 v10, s12, v10
	ds_read_u16 v247, v10 offset:128
	ds_read_u16 v246, v10
	v_add_u32_e32 v10, s12, v10
	ds_read_u16 v249, v10 offset:128
	ds_read_u16 v248, v10
	v_add_u32_e32 v10, s12, v10
	ds_read_u16 v251, v10 offset:128
	ds_read_u16 v250, v10
	v_add_u32_e32 v10, s12, v10
	s_waitcnt lgkmcnt(0)
.LBB0_454:
	s_cmp_eq_u32 s6, 4
	s_cselect_b32 s14, s13, 0
	s_cmp_eq_u32 s6, 8
	s_cselect_b32 s15, s13, 0
	v_add_u32_e32 v10, s14, v10
	v_add_u32_e32 v7, s15, v7
	s_waitcnt lgkmcnt(12)
	v_lshlrev_b32_e32 v245, 16, v245
	v_lshlrev_b32_e32 v244, 16, v244
	v_cvt_pk_bf16_f32 v8, v4, s0
	ds_write_b16 v7, v8
	v_cvt_pk_bf16_f32 v8, v5, s0
	ds_write_b16 v7, v8 offset:128
	v_pk_mul_f32 v[8:9], v[2:3], v[4:5] op_sel:[0,1]
	v_pk_fma_f32 v[12:13], v[0:1], v[4:5], v[8:9] neg_lo:[0,0,1] neg_hi:[0,0,1]
	v_pk_fma_f32 v[4:5], v[0:1], v[4:5], v[8:9] op_sel_hi:[1,0,1]
	v_add_u32_e32 v7, s12, v7
	v_mov_b32_e32 v13, v5
	v_pk_add_f32 v[4:5], v[12:13], v[244:245]
	ds_read_u16 v245, v10 offset:128
	ds_read_u16 v244, v10
	v_add_u32_e32 v10, s12, v10
	s_waitcnt lgkmcnt(12)
	v_lshlrev_b32_e32 v247, 16, v247
	v_lshlrev_b32_e32 v246, 16, v246
	v_cvt_pk_bf16_f32 v8, v4, s0
	ds_write_b16 v7, v8
	v_cvt_pk_bf16_f32 v8, v5, s0
	ds_write_b16 v7, v8 offset:128
	v_pk_mul_f32 v[8:9], v[2:3], v[4:5] op_sel:[0,1]
	v_pk_fma_f32 v[12:13], v[0:1], v[4:5], v[8:9] neg_lo:[0,0,1] neg_hi:[0,0,1]
	v_pk_fma_f32 v[4:5], v[0:1], v[4:5], v[8:9] op_sel_hi:[1,0,1]
	v_add_u32_e32 v7, s12, v7
	v_mov_b32_e32 v13, v5
	v_pk_add_f32 v[4:5], v[12:13], v[246:247]
	ds_read_u16 v247, v10 offset:128
	ds_read_u16 v246, v10
	v_add_u32_e32 v10, s12, v10
	s_waitcnt lgkmcnt(12)
	v_lshlrev_b32_e32 v249, 16, v249
	v_lshlrev_b32_e32 v248, 16, v248
	v_cvt_pk_bf16_f32 v8, v4, s0
	ds_write_b16 v7, v8
	v_cvt_pk_bf16_f32 v8, v5, s0
	ds_write_b16 v7, v8 offset:128
	v_pk_mul_f32 v[8:9], v[2:3], v[4:5] op_sel:[0,1]
	v_pk_fma_f32 v[12:13], v[0:1], v[4:5], v[8:9] neg_lo:[0,0,1] neg_hi:[0,0,1]
	v_pk_fma_f32 v[4:5], v[0:1], v[4:5], v[8:9] op_sel_hi:[1,0,1]
	v_add_u32_e32 v7, s12, v7
	v_mov_b32_e32 v13, v5
	v_pk_add_f32 v[4:5], v[12:13], v[248:249]
	ds_read_u16 v249, v10 offset:128
	ds_read_u16 v248, v10
	v_add_u32_e32 v10, s12, v10
	s_waitcnt lgkmcnt(12)
	v_lshlrev_b32_e32 v251, 16, v251
	v_lshlrev_b32_e32 v250, 16, v250
	v_cvt_pk_bf16_f32 v8, v4, s0
	ds_write_b16 v7, v8
	v_cvt_pk_bf16_f32 v8, v5, s0
	ds_write_b16 v7, v8 offset:128
	v_pk_mul_f32 v[8:9], v[2:3], v[4:5] op_sel:[0,1]
	v_pk_fma_f32 v[12:13], v[0:1], v[4:5], v[8:9] neg_lo:[0,0,1] neg_hi:[0,0,1]
	v_pk_fma_f32 v[4:5], v[0:1], v[4:5], v[8:9] op_sel_hi:[1,0,1]
	v_add_u32_e32 v7, s12, v7
	v_mov_b32_e32 v13, v5
	v_pk_add_f32 v[4:5], v[12:13], v[250:251]
	ds_read_u16 v251, v10 offset:128
	ds_read_u16 v250, v10
	v_add_u32_e32 v10, s12, v10
	s_add_i32 s7, s7, -4
	s_add_i32 s6, s6, 4
	s_cmpk_lg_i32 s6, 0x48
	s_cbranch_scc1 .LBB0_454
	s_waitcnt lgkmcnt(0)
	v_readlane_b32 s72, v255, 23
	v_readlane_b32 s73, v255, 24
